# stagger half the CUs of each XCD by ~4.5us at the start of in-proj and FFN-in GEMM phases (desynchronise epilogue store bursts)
# speedup vs baseline: 1.0038x; 1.0020x over previous
; #define GAS __attribute__((address_space(1)))
; #define PH unsigned char* ws = KA->ws; int L = Lc; asm volatile("" : "+s"(ws), "+s"(L)); const unsigned char* wl = ws + WS_W + (size_t)L * W_LAYER; (void)wl
; __global__ void __launch_bounds__(512, 2) mega_fwd(Args a) {
;     ...
;     for (int Lc = 0; Lc < 2; ++Lc) {
;         {
;             PH;
;             run_gemm(lds, (const bf16_t*)(ws + WS_XB), (const bf16_t*)(wl + WO_IN), T_TOK, NIN, DM, FIn{(GAS bf16_t*)(ws + WS_HA), (GAS float*)(ws + WS_FL), (GAS float*)(ws + WS_IW), (const GAS float*)(ws + WS_TRIG)});
.LBB0_109:
	v_readlane_b32 s2, v252, 42
	s_nop 3
	s_bfe_u32 s2, s2, 0x10003
	s_cmp_eq_u32 s2, 0
	s_cbranch_scc1 .Lstag_P1
	s_sleep 127

; #define GAS __attribute__((address_space(1)))
;     __device__ __forceinline__ bool next(int i, pg8::Unit& o) const { if (i >= 3) return false; o.pm = pm + i * dpm; o.pn = pn + 4 * i; return true; }
;     __device__ __forceinline__ bool next(int i, pg8::Unit& o) const { if (i != 0) return false; o = u; return true; }
; #define GSYNC() do { XcdBarrier xb_; xb_.bar = (unsigned*)(KA->ws + WS_CTL) + 2048; xb_.x = xb_xcc_id(); xb_.st = (volatile LAS unsigned*)(lds + LDS_SLOT + 16); xcd_barrier(xb_); } while (0)
; #define PH unsigned char* ws = KA->ws; int L = Lc; asm volatile("" : "+s"(ws), "+s"(L)); const unsigned char* wl = ws + WS_W + (size_t)L * W_LAYER; (void)wl
;     __host__ __device__ __forceinline__ bool next(int i, Unit& u) const {
;         const long L = (long)i * G + c; if (L >= nwg) return false;
;         int wgid = (int)L; { const int q = nwg / NXCD, r = nwg % NXCD, xcd = wgid % NXCD, off = wgid / NXCD; wgid = (xcd < r ? xcd * (q + 1) : r * (q + 1) + (xcd - r) * q) + off; }
; __global__ void __launch_bounds__(512, 2) mega_fwd(Args a) {
;     ...
;         GSYNC();
;         {
;             PH;
;             run_gemm(lds, (const bf16_t*)(ws + WS_XB), (const bf16_t*)(wl + WO_FF1), T_TOK, NFF1, DM, FFf1{(GAS bf16_t*)(ws + WS_HFF), (GAS bf16_t*)(ws + WS_PG)});
.LBB0_1347:
	s_or_b64 exec, exec, s[0:1]
	s_waitcnt lgkmcnt(0)
	s_barrier
	v_readlane_b32 s2, v252, 42
	s_nop 3
	s_bfe_u32 s2, s2, 0x10003
	s_cmp_eq_u32 s2, 0
	s_cbranch_scc1 .Lstag_P7
	s_sleep 127
.Lstag_P7:
	s_load_dwordx2 s[2:3], s[84:85], 0x88
	v_readlane_b32 s1, v252, 52
	s_movk_i32 s0, 0x400
	s_mov_b32 s4, 0x10000
	s_movk_i32 s5, 0x1400
	s_waitcnt lgkmcnt(0)
	s_ashr_i32 s6, s4, 31
	s_lshr_b32 s6, s6, 24
	s_add_i32 s4, s4, s6
	s_ashr_i32 s23, s4, 8
	s_ashr_i32 s4, s5, 31
	s_lshr_b32 s4, s4, 24
	s_add_i32 s5, s5, s4
	s_ashr_i32 s26, s5, 8
	s_mul_i32 s6, s26, s23
	v_readlane_b32 s4, v252, 6
	v_mov_b32_e32 v20, v230
	v_readlane_b32 s5, v252, 7
	s_mov_b32 s8, s4
	s_cmp_lt_i32 s4, s6
	s_cselect_b64 s[4:5], -1, 0
	s_cmp_ge_i32 s8, s6
	v_readfirstlane_b32 s7, v20
	s_cbranch_scc1 .LBB0_1353
	s_ashr_i32 s8, s6, 31
	s_lshr_b32 s8, s8, 29
	s_add_i32 s8, s6, s8
	s_ashr_i32 s12, s8, 3
	s_and_b32 s8, s8, -8
	s_sub_i32 s13, s6, s8
	s_add_i32 s11, s12, 1
	v_readlane_b32 s8, v252, 11
	s_cmp_ge_i32 s8, s13
	s_mov_b64 s[8:9], -1
	s_cbranch_scc0 .LBB0_1350
	v_readlane_b32 s9, v252, 11
	s_sub_i32 s9, s9, s13
	s_mul_i32 s8, s11, s13
	s_mul_i32 s9, s9, s12
	s_add_i32 s10, s9, s8
	s_mov_b64 s[8:9], 0
